# RES epilogues (out-proj, down-proj): base loads issued in two batches of 16 instead of a load-wait-store ladder
# speedup vs baseline: 1.0018x; 1.0018x over previous
;     __device__ __forceinline__ void operator()(const f32x4 (&acc)[2][2][4][2], const Unit& u, int wr, int wc, int fr, int fq) const {
;         const int row0 = u.pm * BM + wr * 64 + fr; const int col0 = u.pn * BM + wc * 32 + 8 * fq;
; #pragma unroll
;         for (int ai = 0; ai < 2; ++ai)
; #pragma unroll
;             for (int m = 0; m < 4; ++m) {
;                 const size_t roff = (size_t)(row0 + ai * HALF + m * 16) * (size_t)ldc + col0;
; #pragma unroll
;                 for (int bj = 0; bj < 2; ++bj) {
;                     f32x4 v0 = acc[ai][bj][m][0], v1 = acc[ai][bj][m][1];
;                     const size_t off = roff + bj * HALF;
;                     if constexpr (MODE == EPI_RES) {
;                         const f32x4 b0 = *(const f32x4*)(base + off), b1 = *(const f32x4*)(base + off + 4);
;                         *(f32x4*)(outf + off) = b0 + v0; *(f32x4*)(outf + off + 4) = b1 + v1;
.LBB0_729:
	v_lshl_add_u32 v164, s57, 8, v166
	v_lshl_or_b32 v192, s56, 8, v168
	v_ashrrev_i32_e32 v165, 31, v164
	v_ashrrev_i32_e32 v193, 31, v192
	v_readlane_b32 s12, v254, 62
	v_readlane_b32 s13, v254, 63
	v_lshlrev_b64 v[164:165], 10, v[164:165]
	v_lshl_add_u64 v[164:165], v[164:165], 0, v[192:193]
	v_lshlrev_b64 v[164:165], 2, v[164:165]
	v_lshl_add_u64 v[130:131], s[12:13], 0, v[164:165]
	v_lshl_add_u64 v[192:193], s[16:17], 0, v[164:165]
	global_load_dwordx4 v[198:201], v[130:131], off
	global_load_dwordx4 v[202:205], v[130:131], off offset:16
	global_load_dwordx4 v[206:209], v[130:131], off offset:512
	global_load_dwordx4 v[210:213], v[130:131], off offset:528
	s_mov_b64 s[10:11], 0x10000
	v_lshl_add_u64 v[132:133], v[130:131], 0, s[10:11]
	global_load_dwordx4 v[214:217], v[132:133], off
	global_load_dwordx4 v[218:221], v[132:133], off offset:16
	global_load_dwordx4 v[222:225], v[132:133], off offset:512
	global_load_dwordx4 v[226:229], v[132:133], off offset:528
	s_mov_b64 s[10:11], 0x20000
	v_lshl_add_u64 v[132:133], v[130:131], 0, s[10:11]
	global_load_dwordx4 v[230:233], v[132:133], off
	global_load_dwordx4 v[234:237], v[132:133], off offset:16
	global_load_dwordx4 v[238:241], v[132:133], off offset:512
	global_load_dwordx4 v[242:245], v[132:133], off offset:528
	s_mov_b64 s[10:11], 0x30000
	v_lshl_add_u64 v[132:133], v[130:131], 0, s[10:11]
	global_load_dwordx4 v[246:249], v[132:133], off
	global_load_dwordx4 v[186:189], v[132:133], off offset:16
	global_load_dwordx4 v[170:173], v[132:133], off offset:512
	global_load_dwordx4 v[160:163], v[132:133], off offset:528
	s_waitcnt vmcnt(0)
	v_pk_add_f32 v[126:127], v[126:127], v[198:199]
	v_pk_add_f32 v[128:129], v[128:129], v[200:201]
	v_pk_add_f32 v[122:123], v[122:123], v[202:203]
	v_pk_add_f32 v[124:125], v[124:125], v[204:205]
	v_pk_add_f32 v[118:119], v[118:119], v[206:207]
	v_pk_add_f32 v[120:121], v[120:121], v[208:209]
	v_pk_add_f32 v[114:115], v[114:115], v[210:211]
	v_pk_add_f32 v[116:117], v[116:117], v[212:213]
	v_pk_add_f32 v[110:111], v[110:111], v[214:215]
	v_pk_add_f32 v[112:113], v[112:113], v[216:217]
	v_pk_add_f32 v[106:107], v[106:107], v[218:219]
	v_pk_add_f32 v[108:109], v[108:109], v[220:221]
	v_pk_add_f32 v[102:103], v[102:103], v[222:223]
	v_pk_add_f32 v[104:105], v[104:105], v[224:225]
	v_pk_add_f32 v[98:99], v[98:99], v[226:227]
	v_pk_add_f32 v[100:101], v[100:101], v[228:229]
	v_pk_add_f32 v[94:95], v[94:95], v[230:231]
	v_pk_add_f32 v[96:97], v[96:97], v[232:233]
	v_pk_add_f32 v[90:91], v[90:91], v[234:235]
	v_pk_add_f32 v[92:93], v[92:93], v[236:237]
	v_pk_add_f32 v[86:87], v[86:87], v[238:239]
	v_pk_add_f32 v[88:89], v[88:89], v[240:241]
	v_pk_add_f32 v[82:83], v[82:83], v[242:243]
	v_pk_add_f32 v[84:85], v[84:85], v[244:245]
	v_pk_add_f32 v[78:79], v[78:79], v[246:247]
	v_pk_add_f32 v[80:81], v[80:81], v[248:249]
	v_pk_add_f32 v[74:75], v[74:75], v[186:187]
	v_pk_add_f32 v[76:77], v[76:77], v[188:189]
	v_pk_add_f32 v[70:71], v[70:71], v[170:171]
	v_pk_add_f32 v[72:73], v[72:73], v[172:173]
	v_pk_add_f32 v[66:67], v[66:67], v[160:161]
	v_pk_add_f32 v[68:69], v[68:69], v[162:163]
	s_mov_b64 s[10:11], 0x80000
	v_lshl_add_u64 v[132:133], v[130:131], 0, s[10:11]
	global_load_dwordx4 v[198:201], v[132:133], off
	global_load_dwordx4 v[202:205], v[132:133], off offset:16
	global_load_dwordx4 v[206:209], v[132:133], off offset:512
	global_load_dwordx4 v[210:213], v[132:133], off offset:528
	s_mov_b64 s[10:11], 0x90000
	v_lshl_add_u64 v[132:133], v[130:131], 0, s[10:11]
	global_load_dwordx4 v[214:217], v[132:133], off
	global_load_dwordx4 v[218:221], v[132:133], off offset:16
	global_load_dwordx4 v[222:225], v[132:133], off offset:512
	global_load_dwordx4 v[226:229], v[132:133], off offset:528
	s_mov_b64 s[10:11], 0xa0000
	v_lshl_add_u64 v[132:133], v[130:131], 0, s[10:11]
	global_load_dwordx4 v[230:233], v[132:133], off
	global_load_dwordx4 v[234:237], v[132:133], off offset:16
	global_load_dwordx4 v[238:241], v[132:133], off offset:512
	global_load_dwordx4 v[242:245], v[132:133], off offset:528
	s_mov_b64 s[10:11], 0xb0000
	v_lshl_add_u64 v[132:133], v[130:131], 0, s[10:11]
	global_load_dwordx4 v[246:249], v[132:133], off
	global_load_dwordx4 v[186:189], v[132:133], off offset:16
	global_load_dwordx4 v[170:173], v[132:133], off offset:512
	global_load_dwordx4 v[160:163], v[132:133], off offset:528
	global_store_dwordx4 v[192:193], v[126:129], off
	global_store_dwordx4 v[192:193], v[122:125], off offset:16
	global_store_dwordx4 v[192:193], v[118:121], off offset:512
	global_store_dwordx4 v[192:193], v[114:117], off offset:528
	s_mov_b64 s[10:11], 0x10000
	v_lshl_add_u64 v[132:133], v[192:193], 0, s[10:11]
	global_store_dwordx4 v[132:133], v[110:113], off
	global_store_dwordx4 v[132:133], v[106:109], off offset:16
	global_store_dwordx4 v[132:133], v[102:105], off offset:512
	global_store_dwordx4 v[132:133], v[98:101], off offset:528
	s_mov_b64 s[10:11], 0x20000
	v_lshl_add_u64 v[132:133], v[192:193], 0, s[10:11]
	global_store_dwordx4 v[132:133], v[94:97], off
	global_store_dwordx4 v[132:133], v[90:93], off offset:16
	global_store_dwordx4 v[132:133], v[86:89], off offset:512
	global_store_dwordx4 v[132:133], v[82:85], off offset:528
	s_mov_b64 s[10:11], 0x30000
	v_lshl_add_u64 v[132:133], v[192:193], 0, s[10:11]
	global_store_dwordx4 v[132:133], v[78:81], off
	global_store_dwordx4 v[132:133], v[74:77], off offset:16
	global_store_dwordx4 v[132:133], v[70:73], off offset:512
	global_store_dwordx4 v[132:133], v[66:69], off offset:528
	s_waitcnt vmcnt(16)
;     __device__ __forceinline__ void operator()(const f32x4 (&acc)[2][2][4][2], const Unit& u, int wr, int wc, int fr, int fq) const {
;         const int row0 = u.pm * BM + wr * 64 + fr; const int col0 = u.pn * BM + wc * 32 + 8 * fq;
; #pragma unroll
;         for (int ai = 0; ai < 2; ++ai)
; #pragma unroll
;             for (int m = 0; m < 4; ++m) {
;                 const size_t roff = (size_t)(row0 + ai * HALF + m * 16) * (size_t)ldc + col0;
; #pragma unroll
;                 for (int bj = 0; bj < 2; ++bj) {
;                     f32x4 v0 = acc[ai][bj][m][0], v1 = acc[ai][bj][m][1];
;                     const size_t off = roff + bj * HALF;
;                     if constexpr (MODE == EPI_RES) {
;                         const f32x4 b0 = *(const f32x4*)(base + off), b1 = *(const f32x4*)(base + off + 4);
;                         *(f32x4*)(outf + off) = b0 + v0; *(f32x4*)(outf + off + 4) = b1 + v1;
	v_pk_add_f32 v[62:63], v[62:63], v[198:199]
	v_pk_add_f32 v[64:65], v[64:65], v[200:201]
	v_pk_add_f32 v[58:59], v[58:59], v[202:203]
	v_pk_add_f32 v[60:61], v[60:61], v[204:205]
	v_pk_add_f32 v[54:55], v[54:55], v[206:207]
	v_pk_add_f32 v[56:57], v[56:57], v[208:209]
	v_pk_add_f32 v[50:51], v[50:51], v[210:211]
	v_pk_add_f32 v[52:53], v[52:53], v[212:213]
	v_pk_add_f32 v[46:47], v[46:47], v[214:215]
	v_pk_add_f32 v[48:49], v[48:49], v[216:217]
	v_pk_add_f32 v[42:43], v[42:43], v[218:219]
	v_pk_add_f32 v[44:45], v[44:45], v[220:221]
	v_pk_add_f32 v[38:39], v[38:39], v[222:223]
	v_pk_add_f32 v[40:41], v[40:41], v[224:225]
	v_pk_add_f32 v[34:35], v[34:35], v[226:227]
	v_pk_add_f32 v[36:37], v[36:37], v[228:229]
	v_pk_add_f32 v[30:31], v[30:31], v[230:231]
	v_pk_add_f32 v[32:33], v[32:33], v[232:233]
	v_pk_add_f32 v[26:27], v[26:27], v[234:235]
	v_pk_add_f32 v[28:29], v[28:29], v[236:237]
	v_pk_add_f32 v[22:23], v[22:23], v[238:239]
	v_pk_add_f32 v[24:25], v[24:25], v[240:241]
	v_pk_add_f32 v[18:19], v[18:19], v[242:243]
	v_pk_add_f32 v[20:21], v[20:21], v[244:245]
	v_pk_add_f32 v[14:15], v[14:15], v[246:247]
	v_pk_add_f32 v[16:17], v[16:17], v[248:249]
	v_pk_add_f32 v[10:11], v[10:11], v[186:187]
	v_pk_add_f32 v[12:13], v[12:13], v[188:189]
	v_pk_add_f32 v[6:7], v[6:7], v[170:171]
	v_pk_add_f32 v[8:9], v[8:9], v[172:173]
	v_pk_add_f32 v[2:3], v[2:3], v[160:161]
	v_pk_add_f32 v[4:5], v[4:5], v[162:163]
	s_mov_b64 s[10:11], 0x80000
	v_lshl_add_u64 v[132:133], v[192:193], 0, s[10:11]
	global_store_dwordx4 v[132:133], v[62:65], off
	global_store_dwordx4 v[132:133], v[58:61], off offset:16
	global_store_dwordx4 v[132:133], v[54:57], off offset:512
	global_store_dwordx4 v[132:133], v[50:53], off offset:528
	s_mov_b64 s[10:11], 0x90000
	v_lshl_add_u64 v[132:133], v[192:193], 0, s[10:11]
	global_store_dwordx4 v[132:133], v[46:49], off
	global_store_dwordx4 v[132:133], v[42:45], off offset:16
	global_store_dwordx4 v[132:133], v[38:41], off offset:512
	global_store_dwordx4 v[132:133], v[34:37], off offset:528
	s_mov_b64 s[10:11], 0xa0000
	v_lshl_add_u64 v[132:133], v[192:193], 0, s[10:11]
	global_store_dwordx4 v[132:133], v[30:33], off
	global_store_dwordx4 v[132:133], v[26:29], off offset:16
	global_store_dwordx4 v[132:133], v[22:25], off offset:512
	global_store_dwordx4 v[132:133], v[18:21], off offset:528
	s_mov_b64 s[10:11], 0xb0000
	v_lshl_add_u64 v[132:133], v[192:193], 0, s[10:11]
	global_store_dwordx4 v[132:133], v[14:17], off
	global_store_dwordx4 v[132:133], v[10:13], off offset:16
	global_store_dwordx4 v[132:133], v[6:9], off offset:512
	global_store_dwordx4 v[132:133], v[2:5], off offset:528
	s_mov_b64 s[48:49], -1
	s_andn2_b64 vcc, exec, s[38:39]
	s_cbranch_vccnz .LBB0_718
	s_andn2_b64 vcc, exec, s[0:1]
	s_cbranch_vccnz .LBB0_717
	s_barrier
	s_branch .LBB0_717

;     __device__ __forceinline__ void operator()(const f32x4 (&acc)[2][2][4][2], const Unit& u, int wr, int wc, int fr, int fq) const {
;         const int row0 = u.pm * BM + wr * 64 + fr; const int col0 = u.pn * BM + wc * 32 + 8 * fq;
; #pragma unroll
;         for (int ai = 0; ai < 2; ++ai)
; #pragma unroll
;             for (int m = 0; m < 4; ++m) {
;                 const size_t roff = (size_t)(row0 + ai * HALF + m * 16) * (size_t)ldc + col0;
; #pragma unroll
;                 for (int bj = 0; bj < 2; ++bj) {
;                     f32x4 v0 = acc[ai][bj][m][0], v1 = acc[ai][bj][m][1];
;                     const size_t off = roff + bj * HALF;
;                     if constexpr (MODE == EPI_RES) {
;                         const f32x4 b0 = *(const f32x4*)(base + off), b1 = *(const f32x4*)(base + off + 4);
;                         *(f32x4*)(outf + off) = b0 + v0; *(f32x4*)(outf + off + 4) = b1 + v1;
.LBB0_932:
	v_lshl_add_u32 v164, s55, 8, v166
	v_lshl_or_b32 v192, s54, 8, v168
	v_ashrrev_i32_e32 v165, 31, v164
	v_ashrrev_i32_e32 v193, 31, v192
	v_lshlrev_b64 v[164:165], 10, v[164:165]
	v_lshl_add_u64 v[164:165], v[164:165], 0, v[192:193]
	v_lshlrev_b64 v[164:165], 2, v[164:165]
	v_lshl_add_u64 v[130:131], s[16:17], 0, v[164:165]
	v_lshl_add_u64 v[192:193], s[16:17], 0, v[164:165]
	global_load_dwordx4 v[198:201], v[130:131], off
	global_load_dwordx4 v[202:205], v[130:131], off offset:16
	global_load_dwordx4 v[206:209], v[130:131], off offset:512
	global_load_dwordx4 v[210:213], v[130:131], off offset:528
	s_mov_b64 s[10:11], 0x10000
	v_lshl_add_u64 v[132:133], v[130:131], 0, s[10:11]
	global_load_dwordx4 v[214:217], v[132:133], off
	global_load_dwordx4 v[218:221], v[132:133], off offset:16
	global_load_dwordx4 v[222:225], v[132:133], off offset:512
	global_load_dwordx4 v[226:229], v[132:133], off offset:528
	s_mov_b64 s[10:11], 0x20000
	v_lshl_add_u64 v[132:133], v[130:131], 0, s[10:11]
	global_load_dwordx4 v[230:233], v[132:133], off
	global_load_dwordx4 v[234:237], v[132:133], off offset:16
	global_load_dwordx4 v[238:241], v[132:133], off offset:512
	global_load_dwordx4 v[242:245], v[132:133], off offset:528
	s_mov_b64 s[10:11], 0x30000
	v_lshl_add_u64 v[132:133], v[130:131], 0, s[10:11]
	global_load_dwordx4 v[246:249], v[132:133], off
	global_load_dwordx4 v[186:189], v[132:133], off offset:16
	global_load_dwordx4 v[170:173], v[132:133], off offset:512
	global_load_dwordx4 v[160:163], v[132:133], off offset:528
	s_waitcnt vmcnt(0)
	v_pk_add_f32 v[126:127], v[126:127], v[198:199]
	v_pk_add_f32 v[128:129], v[128:129], v[200:201]
	v_pk_add_f32 v[122:123], v[122:123], v[202:203]
	v_pk_add_f32 v[124:125], v[124:125], v[204:205]
	v_pk_add_f32 v[118:119], v[118:119], v[206:207]
	v_pk_add_f32 v[120:121], v[120:121], v[208:209]
	v_pk_add_f32 v[114:115], v[114:115], v[210:211]
	v_pk_add_f32 v[116:117], v[116:117], v[212:213]
	v_pk_add_f32 v[110:111], v[110:111], v[214:215]
	v_pk_add_f32 v[112:113], v[112:113], v[216:217]
	v_pk_add_f32 v[106:107], v[106:107], v[218:219]
	v_pk_add_f32 v[108:109], v[108:109], v[220:221]
	v_pk_add_f32 v[102:103], v[102:103], v[222:223]
	v_pk_add_f32 v[104:105], v[104:105], v[224:225]
	v_pk_add_f32 v[98:99], v[98:99], v[226:227]
	v_pk_add_f32 v[100:101], v[100:101], v[228:229]
	v_pk_add_f32 v[94:95], v[94:95], v[230:231]
	v_pk_add_f32 v[96:97], v[96:97], v[232:233]
	v_pk_add_f32 v[90:91], v[90:91], v[234:235]
	v_pk_add_f32 v[92:93], v[92:93], v[236:237]
	v_pk_add_f32 v[86:87], v[86:87], v[238:239]
	v_pk_add_f32 v[88:89], v[88:89], v[240:241]
	v_pk_add_f32 v[82:83], v[82:83], v[242:243]
	v_pk_add_f32 v[84:85], v[84:85], v[244:245]
	v_pk_add_f32 v[78:79], v[78:79], v[246:247]
	v_pk_add_f32 v[80:81], v[80:81], v[248:249]
	v_pk_add_f32 v[74:75], v[74:75], v[186:187]
	v_pk_add_f32 v[76:77], v[76:77], v[188:189]
	v_pk_add_f32 v[70:71], v[70:71], v[170:171]
	v_pk_add_f32 v[72:73], v[72:73], v[172:173]
	v_pk_add_f32 v[66:67], v[66:67], v[160:161]
	v_pk_add_f32 v[68:69], v[68:69], v[162:163]
	s_mov_b64 s[10:11], 0x80000
	v_lshl_add_u64 v[132:133], v[130:131], 0, s[10:11]
	global_load_dwordx4 v[198:201], v[132:133], off
	global_load_dwordx4 v[202:205], v[132:133], off offset:16
	global_load_dwordx4 v[206:209], v[132:133], off offset:512
	global_load_dwordx4 v[210:213], v[132:133], off offset:528
	s_mov_b64 s[10:11], 0x90000
	v_lshl_add_u64 v[132:133], v[130:131], 0, s[10:11]
	global_load_dwordx4 v[214:217], v[132:133], off
	global_load_dwordx4 v[218:221], v[132:133], off offset:16
	global_load_dwordx4 v[222:225], v[132:133], off offset:512
	global_load_dwordx4 v[226:229], v[132:133], off offset:528
	s_mov_b64 s[10:11], 0xa0000
	v_lshl_add_u64 v[132:133], v[130:131], 0, s[10:11]
	global_load_dwordx4 v[230:233], v[132:133], off
	global_load_dwordx4 v[234:237], v[132:133], off offset:16
	global_load_dwordx4 v[238:241], v[132:133], off offset:512
	global_load_dwordx4 v[242:245], v[132:133], off offset:528
	s_mov_b64 s[10:11], 0xb0000
	v_lshl_add_u64 v[132:133], v[130:131], 0, s[10:11]
	global_load_dwordx4 v[246:249], v[132:133], off
	global_load_dwordx4 v[186:189], v[132:133], off offset:16
	global_load_dwordx4 v[170:173], v[132:133], off offset:512
	global_load_dwordx4 v[160:163], v[132:133], off offset:528
	global_store_dwordx4 v[192:193], v[126:129], off
	global_store_dwordx4 v[192:193], v[122:125], off offset:16
	global_store_dwordx4 v[192:193], v[118:121], off offset:512
	global_store_dwordx4 v[192:193], v[114:117], off offset:528
	s_mov_b64 s[10:11], 0x10000
	v_lshl_add_u64 v[132:133], v[192:193], 0, s[10:11]
	global_store_dwordx4 v[132:133], v[110:113], off
	global_store_dwordx4 v[132:133], v[106:109], off offset:16
	global_store_dwordx4 v[132:133], v[102:105], off offset:512
	global_store_dwordx4 v[132:133], v[98:101], off offset:528
	s_mov_b64 s[10:11], 0x20000
	v_lshl_add_u64 v[132:133], v[192:193], 0, s[10:11]
	global_store_dwordx4 v[132:133], v[94:97], off
	global_store_dwordx4 v[132:133], v[90:93], off offset:16
	global_store_dwordx4 v[132:133], v[86:89], off offset:512
	global_store_dwordx4 v[132:133], v[82:85], off offset:528
	s_mov_b64 s[10:11], 0x30000
	v_lshl_add_u64 v[132:133], v[192:193], 0, s[10:11]
	global_store_dwordx4 v[132:133], v[78:81], off
	global_store_dwordx4 v[132:133], v[74:77], off offset:16
	global_store_dwordx4 v[132:133], v[70:73], off offset:512
	global_store_dwordx4 v[132:133], v[66:69], off offset:528
	s_waitcnt vmcnt(16)
;     __device__ __forceinline__ void operator()(const f32x4 (&acc)[2][2][4][2], const Unit& u, int wr, int wc, int fr, int fq) const {
;     ...
;                 const size_t roff = (size_t)(row0 + ai * HALF + m * 16) * (size_t)ldc + col0;
; #pragma unroll
;                 for (int bj = 0; bj < 2; ++bj) {
;                     f32x4 v0 = acc[ai][bj][m][0], v1 = acc[ai][bj][m][1];
;                     const size_t off = roff + bj * HALF;
;                     if constexpr (MODE == EPI_RES) {
;                         const f32x4 b0 = *(const f32x4*)(base + off), b1 = *(const f32x4*)(base + off + 4);
;                         *(f32x4*)(outf + off) = b0 + v0; *(f32x4*)(outf + off + 4) = b1 + v1;
	v_pk_add_f32 v[62:63], v[62:63], v[198:199]
	v_pk_add_f32 v[64:65], v[64:65], v[200:201]
	v_pk_add_f32 v[58:59], v[58:59], v[202:203]
	v_pk_add_f32 v[60:61], v[60:61], v[204:205]
	v_pk_add_f32 v[54:55], v[54:55], v[206:207]
	v_pk_add_f32 v[56:57], v[56:57], v[208:209]
	v_pk_add_f32 v[50:51], v[50:51], v[210:211]
	v_pk_add_f32 v[52:53], v[52:53], v[212:213]
	v_pk_add_f32 v[46:47], v[46:47], v[214:215]
	v_pk_add_f32 v[48:49], v[48:49], v[216:217]
	v_pk_add_f32 v[42:43], v[42:43], v[218:219]
	v_pk_add_f32 v[44:45], v[44:45], v[220:221]
	v_pk_add_f32 v[38:39], v[38:39], v[222:223]
	v_pk_add_f32 v[40:41], v[40:41], v[224:225]
	v_pk_add_f32 v[34:35], v[34:35], v[226:227]
	v_pk_add_f32 v[36:37], v[36:37], v[228:229]
	v_pk_add_f32 v[30:31], v[30:31], v[230:231]
	v_pk_add_f32 v[32:33], v[32:33], v[232:233]
	v_pk_add_f32 v[26:27], v[26:27], v[234:235]
	v_pk_add_f32 v[28:29], v[28:29], v[236:237]
	v_pk_add_f32 v[22:23], v[22:23], v[238:239]
	v_pk_add_f32 v[24:25], v[24:25], v[240:241]
	v_pk_add_f32 v[18:19], v[18:19], v[242:243]
	v_pk_add_f32 v[20:21], v[20:21], v[244:245]
	v_pk_add_f32 v[14:15], v[14:15], v[246:247]
	v_pk_add_f32 v[16:17], v[16:17], v[248:249]
	v_pk_add_f32 v[10:11], v[10:11], v[186:187]
	v_pk_add_f32 v[12:13], v[12:13], v[188:189]
	v_pk_add_f32 v[6:7], v[6:7], v[170:171]
	v_pk_add_f32 v[8:9], v[8:9], v[172:173]
	v_pk_add_f32 v[2:3], v[2:3], v[160:161]
	v_pk_add_f32 v[4:5], v[4:5], v[162:163]
	s_mov_b64 s[10:11], 0x80000
	v_lshl_add_u64 v[132:133], v[192:193], 0, s[10:11]
	global_store_dwordx4 v[132:133], v[62:65], off
	global_store_dwordx4 v[132:133], v[58:61], off offset:16
	global_store_dwordx4 v[132:133], v[54:57], off offset:512
	global_store_dwordx4 v[132:133], v[50:53], off offset:528
	s_mov_b64 s[10:11], 0x90000
	v_lshl_add_u64 v[132:133], v[192:193], 0, s[10:11]
	global_store_dwordx4 v[132:133], v[46:49], off
	global_store_dwordx4 v[132:133], v[42:45], off offset:16
	global_store_dwordx4 v[132:133], v[38:41], off offset:512
	global_store_dwordx4 v[132:133], v[34:37], off offset:528
	s_mov_b64 s[10:11], 0xa0000
	v_lshl_add_u64 v[132:133], v[192:193], 0, s[10:11]
	global_store_dwordx4 v[132:133], v[30:33], off
	global_store_dwordx4 v[132:133], v[26:29], off offset:16
	global_store_dwordx4 v[132:133], v[22:25], off offset:512
	global_store_dwordx4 v[132:133], v[18:21], off offset:528
	s_mov_b64 s[10:11], 0xb0000
	v_lshl_add_u64 v[132:133], v[192:193], 0, s[10:11]
	global_store_dwordx4 v[132:133], v[14:17], off
	global_store_dwordx4 v[132:133], v[10:13], off offset:16
	global_store_dwordx4 v[132:133], v[6:9], off offset:512
	global_store_dwordx4 v[132:133], v[2:5], off offset:528
	s_mov_b64 s[46:47], -1
	s_andn2_b64 vcc, exec, s[36:37]
	s_cbranch_vccnz .LBB0_921
	s_andn2_b64 vcc, exec, s[0:1]
	s_cbranch_vccnz .LBB0_920
	s_barrier
	s_branch .LBB0_920
